# DSA top-k classification loop rewritten by hand: branch-free, mbcnt prefix, LDS read prefetch (same list order)
# speedup vs baseline: 1.0374x; 1.0289x over previous
; __device__ __forceinline__ void lds_fence() { asm volatile("s_waitcnt lgkmcnt(0)" ::: "memory"); }
; __device__ __forceinline__ unsigned fkey(float s) { const unsigned u = __float_as_uint(s); return (u & 0x80000000u) ? ~u : (u | 0x80000000u); }
; template <bool DUMMY> __device__ __forceinline__ void phase_dsa(const Args& a, unsigned char* lds) {
;     ...
;                     int cs = 0, cc = 0;
;                     for (int i0 = beg + lane * 4; i0 < end; i0 += 256) { const f32x4 v = *(const f32x4*)(sc + i0);
; #pragma unroll
;                         for (int e = 0; e < 4; ++e) { const unsigned k = fkey(v[e]); const unsigned kb = k >> 21;
;                             const bool sure = kb > b1, cand = (kb == b1) && store_c;
;                             const unsigned long long ms = __ballot(sure), mc = __ballot(cand);
;                             if (ms) { const int p = cs + __popcll(ms & ltmask); const int pp = hf ? nsure - 1 - p : p; if (sure && pp >= 0 && pp < 256) list[pp] = i0 + e; cs += __popcll(ms); }
;                             if (mc) { const int p = cc + __popcll(mc & ltmask); const int pp = hf ? c1 - 1 - p : p; if (cand && pp >= 0 && pp < CAP) { hist[2 * pp] = k; hist[2 * pp + 1] = (unsigned)(i0 + e); } cc += __popcll(mc); } } }
;                     lds_fence(); __builtin_amdgcn_s_barrier();
.LBB0_917:
	s_or_b64 exec, exec, s[0:1]
	v_lshlrev_b64 v[10:11], v222, -1
	s_waitcnt lgkmcnt(0)
	s_lshr_b32 s0, s12, 1
	v_not_b32_e32 v120, v10
	v_lshlrev_b32_e32 v10, 2, v222
	s_lshl_b32 s65, s61, 10
	v_not_b32_e32 v8, v11
	v_cmp_gt_u32_e32 vcc, s0, v10
	s_barrier
	s_and_saveexec_b64 s[12:13], vcc
	s_cbranch_execz .LBB0_952
	s_add_i32 s25, s65, 0
	s_mul_i32 s10, s8, s0
	s_add_i32 s25, s25, 0x24080
	s_add_i32 s26, s10, s0
	s_cmp_eq_u32 s8, 0
	s_mul_i32 s1, s61, 0x8020
	s_cselect_b64 s[8:9], -1, 0
	s_lshl_b32 s0, s10, 2
	s_add_i32 s0, s0, s1
	s_add_i32 s0, s0, 0
	v_cmp_gt_i32_e64 s[6:7], s42, v131
	v_add_u32_e32 v11, s10, v10
	s_mov_b32 s27, 0
	v_add_u32_e32 v133, s0, v129
	s_mov_b64 s[14:15], 0
	s_mov_b32 s28, 0
	v_cndmask_b32_e64 v12, -1, 1, s[8:9]
	v_sub_u32_e32 v13, 0xff, v132
	v_add_u32_e32 v14, -1, v131
	v_cndmask_b32_e64 v13, v13, 0, s[8:9]
	v_cndmask_b32_e64 v14, v14, 0, s[8:9]
	ds_read_b128 v[20:23], v133
	s_waitcnt lgkmcnt(0)
.Lcls_loop:
	v_mov_b64_e32 v[16:17], v[20:21]
	v_mov_b64_e32 v[18:19], v[22:23]
	s_mov_b64 s[14:15], exec
	v_add_u32_e32 v133, 0x400, v133
	ds_read_b128 v[20:23], v133
	v_mov_b32_e32 v41, v11
	v_add_u32_e32 v43, 1, v11
	v_add_u32_e32 v45, 2, v11
	v_add_u32_e32 v47, 3, v11
	v_ashrrev_i32_e32 v24, 31, v16
	v_ashrrev_i32_e32 v25, 31, v17
	v_ashrrev_i32_e32 v26, 31, v18
	v_ashrrev_i32_e32 v27, 31, v19
	v_or_b32_e32 v24, 0x80000000, v24
	v_or_b32_e32 v25, 0x80000000, v25
	v_or_b32_e32 v26, 0x80000000, v26
	v_or_b32_e32 v27, 0x80000000, v27
	v_xor_b32_e32 v40, v16, v24
	v_xor_b32_e32 v42, v17, v25
	v_xor_b32_e32 v44, v18, v26
	v_xor_b32_e32 v46, v19, v27
	v_lshrrev_b32_e32 v28, 21, v40
	v_lshrrev_b32_e32 v29, 21, v42
	v_lshrrev_b32_e32 v30, 21, v44
	v_lshrrev_b32_e32 v31, 21, v46
	v_cmp_lt_u32_e64 s[0:1], s24, v28
	v_cmp_lt_u32_e64 s[10:11], s24, v29
	v_cmp_lt_u32_e64 s[16:17], s24, v30
	v_cmp_lt_u32_e64 s[66:67], s24, v31
	v_mbcnt_lo_u32_b32 v32, s0, 0
	v_mbcnt_lo_u32_b32 v33, s10, 0
	v_mbcnt_lo_u32_b32 v34, s16, 0
	v_mbcnt_lo_u32_b32 v35, s66, 0
	v_mbcnt_hi_u32_b32 v32, s1, v32
	v_mbcnt_hi_u32_b32 v33, s11, v33
	v_mbcnt_hi_u32_b32 v34, s17, v34
	v_mbcnt_hi_u32_b32 v35, s67, v35
	s_bcnt1_i32_b64 s98, s[0:1]
	s_bcnt1_i32_b64 s99, s[10:11]
	s_bcnt1_i32_b64 s100, s[16:17]
	s_bcnt1_i32_b64 s101, s[66:67]
	s_add_i32 s98, s98, s27
	s_add_i32 s99, s99, s98
	s_add_i32 s100, s100, s99
	s_add_i32 s101, s101, s100
	v_add_u32_e32 v32, s27, v32
	v_add_u32_e32 v33, s98, v33
	v_add_u32_e32 v34, s99, v34
	v_add_u32_e32 v35, s100, v35
	v_mad_i32_i24 v32, v32, v12, v13
	v_mad_i32_i24 v33, v33, v12, v13
	v_mad_i32_i24 v34, v34, v12, v13
	v_mad_i32_i24 v35, v35, v12, v13
	v_lshl_add_u32 v32, v32, 2, s25
	v_lshl_add_u32 v33, v33, 2, s25
	v_lshl_add_u32 v34, v34, 2, s25
	v_lshl_add_u32 v35, v35, 2, s25
	s_mov_b32 s27, s101
	s_mov_b64 exec, s[0:1]
	ds_write_b32 v32, v41
	s_mov_b64 exec, s[10:11]
	ds_write_b32 v33, v43
	s_mov_b64 exec, s[16:17]
	ds_write_b32 v34, v45
	s_mov_b64 exec, s[66:67]
	ds_write_b32 v35, v47
	s_mov_b64 exec, s[14:15]
	v_cmp_eq_u32_e64 s[0:1], s24, v28
	v_cmp_eq_u32_e64 s[10:11], s24, v29
	v_cmp_eq_u32_e64 s[16:17], s24, v30
	v_cmp_eq_u32_e64 s[66:67], s24, v31
	s_and_b64 s[0:1], s[0:1], s[6:7]
	s_and_b64 s[10:11], s[10:11], s[6:7]
	s_and_b64 s[16:17], s[16:17], s[6:7]
	s_and_b64 s[66:67], s[66:67], s[6:7]
	v_mbcnt_lo_u32_b32 v36, s0, 0
	v_mbcnt_lo_u32_b32 v37, s10, 0
	v_mbcnt_lo_u32_b32 v38, s16, 0
	v_mbcnt_lo_u32_b32 v39, s66, 0
	v_mbcnt_hi_u32_b32 v36, s1, v36
	v_mbcnt_hi_u32_b32 v37, s11, v37
	v_mbcnt_hi_u32_b32 v38, s17, v38
	v_mbcnt_hi_u32_b32 v39, s67, v39
	s_bcnt1_i32_b64 s98, s[0:1]
	s_bcnt1_i32_b64 s99, s[10:11]
	s_bcnt1_i32_b64 s100, s[16:17]
	s_bcnt1_i32_b64 s101, s[66:67]
	s_add_i32 s98, s98, s28
	s_add_i32 s99, s99, s98
	s_add_i32 s100, s100, s99
	s_add_i32 s101, s101, s100
	v_add_u32_e32 v36, s28, v36
	v_add_u32_e32 v37, s98, v37
	v_add_u32_e32 v38, s99, v38
	v_add_u32_e32 v39, s100, v39
	v_mad_i32_i24 v36, v36, v12, v14
	v_mad_i32_i24 v37, v37, v12, v14
	v_mad_i32_i24 v38, v38, v12, v14
	v_mad_i32_i24 v39, v39, v12, v14
	v_lshl_add_u32 v36, v36, 3, s23
	v_lshl_add_u32 v37, v37, 3, s23
	v_lshl_add_u32 v38, v38, 3, s23
	v_lshl_add_u32 v39, v39, 3, s23
	s_mov_b32 s28, s101
	s_mov_b64 exec, s[0:1]
	ds_write_b64 v36, v[40:41]
	s_mov_b64 exec, s[10:11]
	ds_write_b64 v37, v[42:43]
	s_mov_b64 exec, s[16:17]
	ds_write_b64 v38, v[44:45]
	s_mov_b64 exec, s[66:67]
	ds_write_b64 v39, v[46:47]
	s_mov_b64 exec, s[14:15]
	v_add_u32_e32 v11, 0x100, v11
	v_cmp_gt_u32_e64 s[0:1], s26, v11
	s_and_b64 exec, exec, s[0:1]
	s_waitcnt lgkmcnt(8)
	s_cbranch_execnz .Lcls_loop

; __global__ void __launch_bounds__(512, 2) mega_fwd(Args a) {
;     extern __shared__ __attribute__((aligned(16))) unsigned char lds[];
	.amdhsa_kernel _Z8mega_fwd4Args
		.amdhsa_group_segment_fixed_size 0
		.amdhsa_private_segment_fixed_size 0
		.amdhsa_kernarg_size 464
		.amdhsa_user_sgpr_count 2
		.amdhsa_user_sgpr_dispatch_ptr 0
		.amdhsa_user_sgpr_queue_ptr 0
		.amdhsa_user_sgpr_kernarg_segment_ptr 1
		.amdhsa_user_sgpr_dispatch_id 0
		.amdhsa_user_sgpr_kernarg_preload_length 0
		.amdhsa_user_sgpr_kernarg_preload_offset 0
		.amdhsa_user_sgpr_private_segment_size 0
		.amdhsa_uses_dynamic_stack 0
		.amdhsa_enable_private_segment 0
		.amdhsa_system_sgpr_workgroup_id_x 1
		.amdhsa_system_sgpr_workgroup_id_y 0
		.amdhsa_system_sgpr_workgroup_id_z 0
		.amdhsa_system_sgpr_workgroup_info 0
		.amdhsa_system_vgpr_workitem_id 2
		.amdhsa_next_free_vgpr 254
		.amdhsa_next_free_sgpr 102
		.amdhsa_accum_offset 256
		.amdhsa_reserve_vcc 1
		.amdhsa_float_round_mode_32 0
		.amdhsa_float_round_mode_16_64 0
		.amdhsa_float_denorm_mode_32 3
		.amdhsa_float_denorm_mode_16_64 3
		.amdhsa_dx10_clamp 1
		.amdhsa_ieee_mode 1
		.amdhsa_fp16_overflow 0
		.amdhsa_tg_split 0
		.amdhsa_exception_fp_ieee_invalid_op 0
		.amdhsa_exception_fp_denorm_src 0
		.amdhsa_exception_fp_ieee_div_zero 0
		.amdhsa_exception_fp_ieee_overflow 0
		.amdhsa_exception_fp_ieee_underflow 0
		.amdhsa_exception_fp_ieee_inexact 0
		.amdhsa_exception_int_div_zero 0
	.end_amdhsa_kernel

; __global__ void __launch_bounds__(512, 2) mega_fwd(Args a) {
;     extern __shared__ __attribute__((aligned(16))) unsigned char lds[];
amdhsa.kernels:
  - .agpr_count:     0
    .args:
      - .offset:         0
        .size:           208
        .value_kind:     by_value
      - .offset:         208
        .size:           4
        .value_kind:     hidden_block_count_x
      - .offset:         212
        .size:           4
        .value_kind:     hidden_block_count_y
      - .offset:         216
        .size:           4
        .value_kind:     hidden_block_count_z
      - .offset:         220
        .size:           2
        .value_kind:     hidden_group_size_x
      - .offset:         222
        .size:           2
        .value_kind:     hidden_group_size_y
      - .offset:         224
        .size:           2
        .value_kind:     hidden_group_size_z
      - .offset:         226
        .size:           2
        .value_kind:     hidden_remainder_x
      - .offset:         228
        .size:           2
        .value_kind:     hidden_remainder_y
      - .offset:         230
        .size:           2
        .value_kind:     hidden_remainder_z
      - .offset:         248
        .size:           8
        .value_kind:     hidden_global_offset_x
      - .offset:         256
        .size:           8
        .value_kind:     hidden_global_offset_y
      - .offset:         264
        .size:           8
        .value_kind:     hidden_global_offset_z
      - .offset:         272
        .size:           2
        .value_kind:     hidden_grid_dims
      - .offset:         296
        .size:           8
        .value_kind:     hidden_multigrid_sync_arg
      - .offset:         328
        .size:           4
        .value_kind:     hidden_dynamic_lds_size
    .group_segment_fixed_size: 0
    .kernarg_segment_align: 8
    .kernarg_segment_size: 464
    .language:       OpenCL C
    .language_version:
      - 2
      - 0
    .max_flat_workgroup_size: 512
    .name:           _Z8mega_fwd4Args
    .private_segment_fixed_size: 0
    .sgpr_count:     108
    .sgpr_spill_count: 0
    .symbol:         _Z8mega_fwd4Args.kd
    .uniform_work_group_size: 1
    .uses_dynamic_stack: false
    .vgpr_count:     254
    .vgpr_spill_count: 0
    .wavefront_size: 64
